# EpiVT rstd butterfly via DPP instead of ds_bpermute (on top of rstd cache)
# baseline (speedup 1.0000x reference)
; DI unsigned pk2(float lo, float hi) { return pg8::cvt_pk_bf16(lo, hi); }
;     DI void operator()(const f32x4 (&acc)[2][2][4][2], const pg8::Unit& u, int wr, int wc, int fr, int fq) const {
;         const int row0 = u.pm * 256 + wr * 64 + fr, tok0 = u.pn * 256 + wc * 32 + 8 * fq;
; #pragma unroll
;         for (int bj = 0; bj < 2; ++bj) {
;             float rs[8];
; #pragma unroll
;             for (int j = 0; j < 8; ++j) {
;                 float s = ssq[(size_t)(tok0 + bj * 128 + j) * 16 + fr];
;                 s += __shfl_xor(s, 1); s += __shfl_xor(s, 2); s += __shfl_xor(s, 4); s += __shfl_xor(s, 8);
;                 rs[j] = rsqrtf(s * (1.0f / DM) + EPS);
;             }
; #pragma unroll
;             for (int ai = 0; ai < 2; ++ai)
; #pragma unroll
;                 for (int m = 0; m < 4; ++m) {
;                     const f32x4 a = acc[ai][bj][m][0], b = acc[ai][bj][m][1];
;                     u32x4 w; w.x = pk2(a[0] * rs[0], a[1] * rs[1]); w.y = pk2(a[2] * rs[2], a[3] * rs[3]); w.z = pk2(b[0] * rs[4], b[1] * rs[5]); w.w = pk2(b[2] * rs[6], b[3] * rs[7]);
;                     *(u32x4*)(VT + ((size_t)((tok0 + bj * 128) >> 3) * 1024 + (row0 + ai * 128 + m * 16)) * 8) = w;
;                 }
;         }
.LBB0_435:
	v_and_b32_e32 v143, 64, v194
	v_xor_b32_e32 v142, 1, v194
	v_add_u32_e32 v143, 64, v143
	v_cmp_lt_i32_e32 vcc, v142, v143
	v_lshl_or_b32 v144, s57, 8, v160
	v_or_b32_e32 v148, 1, v144
	v_cndmask_b32_e32 v142, v194, v142, vcc
	v_lshlrev_b32_e32 v179, 2, v142
	v_xor_b32_e32 v142, 2, v194
	v_cmp_lt_i32_e32 vcc, v142, v143
	v_ashrrev_i32_e32 v145, 31, v144
	v_ashrrev_i32_e32 v149, 31, v148
	v_cndmask_b32_e32 v142, v194, v142, vcc
	v_lshlrev_b32_e32 v178, 2, v142
	v_xor_b32_e32 v142, 4, v194
	v_cmp_lt_i32_e32 vcc, v142, v143
	v_lshlrev_b64 v[148:149], 6, v[148:149]
	v_lshl_add_u64 v[148:149], v[136:137], 0, v[148:149]
	v_cndmask_b32_e32 v142, v194, v142, vcc
	v_lshlrev_b32_e32 v163, 2, v142
	v_xor_b32_e32 v142, 8, v194
	v_cmp_lt_i32_e32 vcc, v142, v143
	v_lshl_add_u32 v146, s58, 8, v158
	v_ashrrev_i32_e32 v147, 31, v146
	v_cndmask_b32_e32 v142, v194, v142, vcc
	v_lshlrev_b32_e32 v162, 2, v142
	v_lshlrev_b64 v[142:143], 6, v[144:145]
	v_lshl_add_u64 v[142:143], v[136:137], 0, v[142:143]
	global_load_dword v142, v[142:143], off
	v_readlane_b32 s12, v246, 60
	global_load_dword v143, v[148:149], off
	v_or_b32_e32 v148, 2, v144
	v_ashrrev_i32_e32 v149, 31, v148
	v_lshlrev_b64 v[148:149], 6, v[148:149]
	v_lshl_add_u64 v[148:149], v[136:137], 0, v[148:149]
	global_load_dword v154, v[148:149], off
	v_or_b32_e32 v148, 3, v144
	v_ashrrev_i32_e32 v149, 31, v148
	v_lshlrev_b64 v[148:149], 6, v[148:149]
	v_lshl_add_u64 v[148:149], v[136:137], 0, v[148:149]
	global_load_dword v155, v[148:149], off
	v_or_b32_e32 v148, 4, v144
	v_ashrrev_i32_e32 v149, 31, v148
	v_lshlrev_b64 v[148:149], 6, v[148:149]
	v_lshl_add_u64 v[148:149], v[136:137], 0, v[148:149]
	global_load_dword v156, v[148:149], off
	v_or_b32_e32 v148, 5, v144
	v_ashrrev_i32_e32 v149, 31, v148
	v_lshlrev_b64 v[148:149], 6, v[148:149]
	v_lshl_add_u64 v[148:149], v[136:137], 0, v[148:149]
	global_load_dword v157, v[148:149], off
	v_or_b32_e32 v148, 6, v144
	v_ashrrev_i32_e32 v149, 31, v148
	v_lshlrev_b64 v[148:149], 6, v[148:149]
	v_lshl_add_u64 v[148:149], v[136:137], 0, v[148:149]
	global_load_dword v152, v[148:149], off
	v_or_b32_e32 v148, 7, v144
	v_ashrrev_i32_e32 v149, 31, v148
	v_lshlrev_b64 v[148:149], 6, v[148:149]
	v_lshl_add_u64 v[148:149], v[136:137], 0, v[148:149]
	global_load_dword v153, v[148:149], off
	v_ashrrev_i32_e32 v148, 3, v144
	v_ashrrev_i32_e32 v149, 31, v148
	v_lshlrev_b64 v[150:151], 14, v[148:149]
	v_readlane_b32 s13, v246, 61
	s_waitcnt vmcnt(0)
	s_nop 1
	v_mov_b32_dpp v148, v142 quad_perm:[1,0,3,2] row_mask:0xf bank_mask:0xf
	v_mov_b32_dpp v149, v143 quad_perm:[1,0,3,2] row_mask:0xf bank_mask:0xf
	s_waitcnt lgkmcnt(0)
	v_pk_add_f32 v[142:143], v[142:143], v[148:149]
	s_nop 1
	v_mov_b32_dpp v148, v142 quad_perm:[2,3,0,1] row_mask:0xf bank_mask:0xf
	v_mov_b32_dpp v149, v143 quad_perm:[2,3,0,1] row_mask:0xf bank_mask:0xf
	s_waitcnt lgkmcnt(0)
	v_pk_add_f32 v[142:143], v[142:143], v[148:149]
	s_nop 1
	v_mov_b32_dpp v148, v142 row_half_mirror row_mask:0xf bank_mask:0xf
	v_mov_b32_dpp v149, v143 row_half_mirror row_mask:0xf bank_mask:0xf
	s_waitcnt lgkmcnt(0)
	v_pk_add_f32 v[142:143], v[142:143], v[148:149]
	s_nop 1
	v_mov_b32_dpp v148, v142 row_mirror row_mask:0xf bank_mask:0xf
	v_mov_b32_dpp v149, v143 row_mirror row_mask:0xf bank_mask:0xf
	s_waitcnt lgkmcnt(0)
	v_pk_add_f32 v[148:149], v[142:143], v[148:149]
	v_mov_b64_e32 v[142:143], s[16:17]
	v_pk_fma_f32 v[148:149], v[148:149], s[34:35], v[142:143] op_sel_hi:[1,0,0]
	s_nop 0
	v_mul_f32_e32 v145, 0x4b800000, v148
	v_cmp_gt_f32_e64 s[2:3], s25, v148
	v_cmp_gt_f32_e32 vcc, s25, v149
	s_nop 0
	v_cndmask_b32_e64 v145, v148, v145, s[2:3]
	v_rsq_f32_e32 v148, v145
	v_mul_f32_e32 v145, 0x4b800000, v149
	v_cndmask_b32_e32 v145, v149, v145, vcc
	v_rsq_f32_e32 v149, v145
	s_nop 0
	v_pk_mul_f32 v[180:181], v[148:149], s[26:27] op_sel_hi:[1,0]
	s_nop 0
	v_cndmask_b32_e32 v149, v149, v181, vcc
	v_cndmask_b32_e64 v148, v148, v180, s[2:3]
	s_nop 1
	v_mov_b32_dpp v180, v154 quad_perm:[1,0,3,2] row_mask:0xf bank_mask:0xf
	v_mov_b32_dpp v181, v155 quad_perm:[1,0,3,2] row_mask:0xf bank_mask:0xf
	v_pk_mul_f32 v[126:127], v[126:127], v[148:149]
	v_pk_mul_f32 v[94:95], v[94:95], v[148:149]
	v_cvt_pk_bf16_f32 v126, v126, v127
	v_cvt_pk_bf16_f32 v94, v94, v95
	s_waitcnt lgkmcnt(0)
	v_pk_add_f32 v[154:155], v[154:155], v[180:181]
	s_nop 1
	v_mov_b32_dpp v180, v154 quad_perm:[2,3,0,1] row_mask:0xf bank_mask:0xf
	v_mov_b32_dpp v181, v155 quad_perm:[2,3,0,1] row_mask:0xf bank_mask:0xf
	v_pk_mul_f32 v[86:87], v[86:87], v[148:149]
	v_pk_mul_f32 v[78:79], v[78:79], v[148:149]
	v_cvt_pk_bf16_f32 v86, v86, v87
	v_cvt_pk_bf16_f32 v78, v78, v79
	s_waitcnt lgkmcnt(0)
	v_pk_add_f32 v[154:155], v[154:155], v[180:181]
	s_nop 1
	v_mov_b32_dpp v180, v154 row_half_mirror row_mask:0xf bank_mask:0xf
	v_mov_b32_dpp v181, v155 row_half_mirror row_mask:0xf bank_mask:0xf
	v_pk_mul_f32 v[70:71], v[70:71], v[148:149]
	v_pk_mul_f32 v[118:119], v[118:119], v[148:149]
	v_pk_mul_f32 v[110:111], v[110:111], v[148:149]
	v_pk_mul_f32 v[102:103], v[102:103], v[148:149]
	s_waitcnt lgkmcnt(0)
	v_pk_add_f32 v[154:155], v[154:155], v[180:181]
	s_nop 1
	v_mov_b32_dpp v180, v154 row_mirror row_mask:0xf bank_mask:0xf
	v_mov_b32_dpp v181, v155 row_mirror row_mask:0xf bank_mask:0xf
	v_cvt_pk_bf16_f32 v70, v70, v71
	v_cvt_pk_bf16_f32 v118, v118, v119
	v_cvt_pk_bf16_f32 v110, v110, v111
	v_cvt_pk_bf16_f32 v102, v102, v103
	s_waitcnt lgkmcnt(0)
; DI unsigned pk2(float lo, float hi) { return pg8::cvt_pk_bf16(lo, hi); }
;     DI void operator()(const f32x4 (&acc)[2][2][4][2], const pg8::Unit& u, int wr, int wc, int fr, int fq) const {
;     ...
;             float rs[8];
; #pragma unroll
;             for (int j = 0; j < 8; ++j) {
;                 float s = ssq[(size_t)(tok0 + bj * 128 + j) * 16 + fr];
;                 s += __shfl_xor(s, 1); s += __shfl_xor(s, 2); s += __shfl_xor(s, 4); s += __shfl_xor(s, 8);
;                 rs[j] = rsqrtf(s * (1.0f / DM) + EPS);
;             }
; #pragma unroll
;             for (int ai = 0; ai < 2; ++ai)
; #pragma unroll
;                 for (int m = 0; m < 4; ++m) {
;                     const f32x4 a = acc[ai][bj][m][0], b = acc[ai][bj][m][1];
;                     u32x4 w; w.x = pk2(a[0] * rs[0], a[1] * rs[1]); w.y = pk2(a[2] * rs[2], a[3] * rs[3]); w.z = pk2(b[0] * rs[4], b[1] * rs[5]); w.w = pk2(b[2] * rs[6], b[3] * rs[7]);
;                     *(u32x4*)(VT + ((size_t)((tok0 + bj * 128) >> 3) * 1024 + (row0 + ai * 128 + m * 16)) * 8) = w;
;                 }
	v_pk_add_f32 v[154:155], v[154:155], v[180:181]
	s_nop 0
	v_pk_fma_f32 v[154:155], v[154:155], s[34:35], v[142:143] op_sel_hi:[1,0,0]
	s_nop 0
	v_mul_f32_e32 v127, 0x4b800000, v154
	v_cmp_gt_f32_e64 s[2:3], s25, v154
	v_cmp_gt_f32_e32 vcc, s25, v155
	s_nop 0
	v_cndmask_b32_e64 v127, v154, v127, s[2:3]
	v_rsq_f32_e32 v154, v127
	v_mul_f32_e32 v127, 0x4b800000, v155
	v_cndmask_b32_e32 v127, v155, v127, vcc
	v_rsq_f32_e32 v155, v127
	s_nop 0
	v_pk_mul_f32 v[180:181], v[154:155], s[26:27] op_sel_hi:[1,0]
	s_nop 0
	v_cndmask_b32_e32 v155, v155, v181, vcc
	v_cndmask_b32_e64 v154, v154, v180, s[2:3]
	v_pk_mul_f32 v[128:129], v[128:129], v[154:155]
	v_pk_mul_f32 v[96:97], v[96:97], v[154:155]
	v_cvt_pk_bf16_f32 v127, v128, v129
	s_nop 1
	v_mov_b32_dpp v128, v156 quad_perm:[1,0,3,2] row_mask:0xf bank_mask:0xf
	v_mov_b32_dpp v129, v157 quad_perm:[1,0,3,2] row_mask:0xf bank_mask:0xf
	v_cvt_pk_bf16_f32 v95, v96, v97
	v_pk_mul_f32 v[88:89], v[88:89], v[154:155]
	v_pk_mul_f32 v[80:81], v[80:81], v[154:155]
	v_cvt_pk_bf16_f32 v87, v88, v89
	s_waitcnt lgkmcnt(0)
	v_pk_add_f32 v[128:129], v[156:157], v[128:129]
	s_nop 1
	v_mov_b32_dpp v156, v128 quad_perm:[2,3,0,1] row_mask:0xf bank_mask:0xf
	v_mov_b32_dpp v157, v129 quad_perm:[2,3,0,1] row_mask:0xf bank_mask:0xf
	v_cvt_pk_bf16_f32 v79, v80, v81
	v_pk_mul_f32 v[72:73], v[72:73], v[154:155]
	v_pk_mul_f32 v[120:121], v[120:121], v[154:155]
	v_pk_mul_f32 v[112:113], v[112:113], v[154:155]
	s_waitcnt lgkmcnt(0)
	v_pk_add_f32 v[128:129], v[128:129], v[156:157]
	s_nop 1
	v_mov_b32_dpp v156, v128 row_half_mirror row_mask:0xf bank_mask:0xf
	v_mov_b32_dpp v157, v129 row_half_mirror row_mask:0xf bank_mask:0xf
	v_pk_mul_f32 v[104:105], v[104:105], v[154:155]
	v_cvt_pk_bf16_f32 v71, v72, v73
	v_cvt_pk_bf16_f32 v119, v120, v121
	v_cvt_pk_bf16_f32 v111, v112, v113
	s_waitcnt lgkmcnt(0)
	v_pk_add_f32 v[128:129], v[128:129], v[156:157]
	s_nop 1
	v_mov_b32_dpp v156, v128 row_mirror row_mask:0xf bank_mask:0xf
	v_mov_b32_dpp v157, v129 row_mirror row_mask:0xf bank_mask:0xf
	v_cvt_pk_bf16_f32 v103, v104, v105
	s_waitcnt lgkmcnt(0)
	v_pk_add_f32 v[128:129], v[128:129], v[156:157]
	s_nop 0
	v_pk_fma_f32 v[128:129], v[128:129], s[34:35], v[142:143] op_sel_hi:[1,0,0]
	s_nop 0
	v_mul_f32_e32 v145, 0x4b800000, v128
	v_cmp_gt_f32_e64 s[2:3], s25, v128
	v_cmp_gt_f32_e32 vcc, s25, v129
	s_nop 0
	v_cndmask_b32_e64 v128, v128, v145, s[2:3]
	v_mul_f32_e32 v145, 0x4b800000, v129
	v_cndmask_b32_e32 v129, v129, v145, vcc
	v_rsq_f32_e32 v128, v128
	v_rsq_f32_e32 v129, v129
	s_nop 0
	v_pk_mul_f32 v[156:157], v[128:129], s[26:27] op_sel_hi:[1,0]
	s_nop 0
	v_cndmask_b32_e32 v157, v129, v157, vcc
	v_cndmask_b32_e64 v156, v128, v156, s[2:3]
	v_pk_mul_f32 v[122:123], v[122:123], v[156:157]
	v_pk_mul_f32 v[90:91], v[90:91], v[156:157]
	v_cvt_pk_bf16_f32 v128, v122, v123
	s_nop 1
	v_mov_b32_dpp v122, v152 quad_perm:[1,0,3,2] row_mask:0xf bank_mask:0xf
	v_mov_b32_dpp v123, v153 quad_perm:[1,0,3,2] row_mask:0xf bank_mask:0xf
	v_cvt_pk_bf16_f32 v96, v90, v91
	v_pk_mul_f32 v[82:83], v[82:83], v[156:157]
	v_pk_mul_f32 v[74:75], v[74:75], v[156:157]
	v_cvt_pk_bf16_f32 v88, v82, v83
	s_waitcnt lgkmcnt(0)
	v_pk_add_f32 v[122:123], v[152:153], v[122:123]
	s_nop 1
	v_mov_b32_dpp v152, v122 quad_perm:[2,3,0,1] row_mask:0xf bank_mask:0xf
	v_mov_b32_dpp v153, v123 quad_perm:[2,3,0,1] row_mask:0xf bank_mask:0xf
	v_cvt_pk_bf16_f32 v80, v74, v75
	v_pk_mul_f32 v[66:67], v[66:67], v[156:157]
	v_pk_mul_f32 v[114:115], v[114:115], v[156:157]
	v_pk_mul_f32 v[106:107], v[106:107], v[156:157]
	s_waitcnt lgkmcnt(0)
	v_pk_add_f32 v[122:123], v[122:123], v[152:153]
	s_nop 1
	v_mov_b32_dpp v152, v122 row_half_mirror row_mask:0xf bank_mask:0xf
	v_mov_b32_dpp v153, v123 row_half_mirror row_mask:0xf bank_mask:0xf
	v_pk_mul_f32 v[98:99], v[98:99], v[156:157]
	v_cvt_pk_bf16_f32 v72, v66, v67
	v_cvt_pk_bf16_f32 v120, v114, v115
	v_cvt_pk_bf16_f32 v112, v106, v107
	s_waitcnt lgkmcnt(0)
	v_pk_add_f32 v[122:123], v[122:123], v[152:153]
	s_nop 1
	v_mov_b32_dpp v152, v122 row_mirror row_mask:0xf bank_mask:0xf
	v_mov_b32_dpp v153, v123 row_mirror row_mask:0xf bank_mask:0xf
	v_cvt_pk_bf16_f32 v104, v98, v99
	s_waitcnt lgkmcnt(0)
	v_pk_add_f32 v[122:123], v[122:123], v[152:153]
	s_nop 0
	v_pk_fma_f32 v[122:123], v[122:123], s[34:35], v[142:143] op_sel_hi:[1,0,0]
	s_nop 0
	v_mul_f32_e32 v129, 0x4b800000, v122
	v_cmp_gt_f32_e64 s[2:3], s25, v122
	v_cmp_gt_f32_e32 vcc, s25, v123
	s_nop 0
	v_cndmask_b32_e64 v122, v122, v129, s[2:3]
	v_mul_f32_e32 v129, 0x4b800000, v123
	v_cndmask_b32_e32 v123, v123, v129, vcc
	v_rsq_f32_e32 v122, v122
	v_rsq_f32_e32 v123, v123
	s_nop 0
	v_pk_mul_f32 v[152:153], v[122:123], s[26:27] op_sel_hi:[1,0]
	s_nop 0
	v_cndmask_b32_e32 v153, v123, v153, vcc
	v_cndmask_b32_e64 v152, v122, v152, s[2:3]
	v_pk_mul_f32 v[122:123], v[124:125], v[152:153]
	v_pk_mul_f32 v[90:91], v[92:93], v[152:153]
	v_cvt_pk_bf16_f32 v129, v122, v123
	v_lshlrev_b64 v[122:123], 4, v[146:147]
	s_mov_b64 s[2:3], 0x800
	v_cvt_pk_bf16_f32 v97, v90, v91
	v_lshl_add_u64 v[90:91], v[122:123], 0, s[2:3]
	v_pk_mul_f32 v[82:83], v[84:85], v[152:153]
	s_mov_b64 s[2:3], 0x900
	v_cvt_pk_bf16_f32 v89, v82, v83
	v_lshl_add_u64 v[82:83], v[122:123], 0, s[2:3]
	v_pk_mul_f32 v[74:75], v[76:77], v[152:153]
	s_mov_b64 s[2:3], 0xa00
	v_cvt_pk_bf16_f32 v81, v74, v75
	v_lshl_add_u64 v[74:75], v[122:123], 0, s[2:3]
	v_pk_mul_f32 v[66:67], v[68:69], v[152:153]
	s_mov_b64 s[2:3], 0xb00
	v_lshl_add_u64 v[124:125], s[12:13], 0, v[150:151]
	v_pk_mul_f32 v[114:115], v[116:117], v[152:153]
	v_pk_mul_f32 v[106:107], v[108:109], v[152:153]
	v_pk_mul_f32 v[98:99], v[100:101], v[152:153]
	v_cvt_pk_bf16_f32 v73, v66, v67
; DI unsigned pk2(float lo, float hi) { return pg8::cvt_pk_bf16(lo, hi); }
;     DI void operator()(const f32x4 (&acc)[2][2][4][2], const pg8::Unit& u, int wr, int wc, int fr, int fq) const {
;     ...
;         for (int bj = 0; bj < 2; ++bj) {
;             float rs[8];
; #pragma unroll
;             for (int j = 0; j < 8; ++j) {
;                 float s = ssq[(size_t)(tok0 + bj * 128 + j) * 16 + fr];
;                 s += __shfl_xor(s, 1); s += __shfl_xor(s, 2); s += __shfl_xor(s, 4); s += __shfl_xor(s, 8);
;                 rs[j] = rsqrtf(s * (1.0f / DM) + EPS);
;             }
; #pragma unroll
;             for (int ai = 0; ai < 2; ++ai)
; #pragma unroll
;                 for (int m = 0; m < 4; ++m) {
;                     const f32x4 a = acc[ai][bj][m][0], b = acc[ai][bj][m][1];
;                     u32x4 w; w.x = pk2(a[0] * rs[0], a[1] * rs[1]); w.y = pk2(a[2] * rs[2], a[3] * rs[3]); w.z = pk2(b[0] * rs[4], b[1] * rs[5]); w.w = pk2(b[2] * rs[6], b[3] * rs[7]);
;                     *(u32x4*)(VT + ((size_t)((tok0 + bj * 128) >> 3) * 1024 + (row0 + ai * 128 + m * 16)) * 8) = w;
;                 }
;         }
	v_lshl_add_u64 v[66:67], v[122:123], 0, s[2:3]
	v_cvt_pk_bf16_f32 v121, v114, v115
	v_or_b32_e32 v114, 16, v146
	v_cvt_pk_bf16_f32 v113, v106, v107
	v_or_b32_e32 v106, 32, v146
	v_cvt_pk_bf16_f32 v105, v98, v99
	v_or_b32_e32 v98, 48, v146
	v_lshl_add_u64 v[68:69], v[124:125], 0, v[66:67]
	v_ashrrev_i32_e32 v115, 31, v114
	v_ashrrev_i32_e32 v107, 31, v106
	v_ashrrev_i32_e32 v99, 31, v98
	global_store_dwordx4 v[68:69], v[70:73], off
	v_or_b32_e32 v68, 0x80, v144
	v_lshlrev_b64 v[114:115], 4, v[114:115]
	v_lshlrev_b64 v[106:107], 4, v[106:107]
	v_lshlrev_b64 v[98:99], 4, v[98:99]
	v_ashrrev_i32_e32 v69, 31, v68
	v_lshl_add_u64 v[150:151], v[124:125], 0, v[122:123]
	v_lshl_add_u64 v[116:117], v[124:125], 0, v[114:115]
	v_lshl_add_u64 v[108:109], v[124:125], 0, v[106:107]
	v_lshl_add_u64 v[100:101], v[124:125], 0, v[98:99]
	v_lshl_add_u64 v[92:93], v[124:125], 0, v[90:91]
	v_lshl_add_u64 v[84:85], v[124:125], 0, v[82:83]
	v_lshl_add_u64 v[76:77], v[124:125], 0, v[74:75]
	v_lshlrev_b64 v[70:71], 6, v[68:69]
	global_store_dwordx4 v[150:151], v[126:129], off
	global_store_dwordx4 v[116:117], v[118:121], off
	global_store_dwordx4 v[108:109], v[110:113], off
	global_store_dwordx4 v[100:101], v[102:105], off
	global_store_dwordx4 v[92:93], v[94:97], off
	global_store_dwordx4 v[84:85], v[86:89], off
	global_store_dwordx4 v[76:77], v[78:81], off
	v_lshl_add_u64 v[70:71], v[136:137], 0, v[70:71]
	global_load_dword v76, v[70:71], off
	v_or_b32_e32 v70, 0x81, v144
	v_ashrrev_i32_e32 v71, 31, v70
	v_lshlrev_b64 v[70:71], 6, v[70:71]
	v_lshl_add_u64 v[70:71], v[136:137], 0, v[70:71]
	global_load_dword v77, v[70:71], off
	v_or_b32_e32 v70, 0x82, v144
	v_ashrrev_i32_e32 v71, 31, v70
	v_lshlrev_b64 v[70:71], 6, v[70:71]
	v_lshl_add_u64 v[70:71], v[136:137], 0, v[70:71]
	global_load_dword v80, v[70:71], off
	v_or_b32_e32 v70, 0x83, v144
	v_ashrrev_i32_e32 v71, 31, v70
	v_lshlrev_b64 v[70:71], 6, v[70:71]
	v_lshl_add_u64 v[70:71], v[136:137], 0, v[70:71]
	global_load_dword v81, v[70:71], off
	v_or_b32_e32 v70, 0x84, v144
	v_ashrrev_i32_e32 v71, 31, v70
	v_lshlrev_b64 v[70:71], 6, v[70:71]
	v_lshl_add_u64 v[70:71], v[136:137], 0, v[70:71]
	global_load_dword v78, v[70:71], off
	v_or_b32_e32 v70, 0x85, v144
	v_ashrrev_i32_e32 v71, 31, v70
	v_lshlrev_b64 v[70:71], 6, v[70:71]
	v_lshl_add_u64 v[70:71], v[136:137], 0, v[70:71]
	global_load_dword v79, v[70:71], off
	v_or_b32_e32 v70, 0x86, v144
	v_ashrrev_i32_e32 v71, 31, v70
	v_lshlrev_b64 v[70:71], 6, v[70:71]
	v_lshl_add_u64 v[70:71], v[136:137], 0, v[70:71]
	global_load_dword v72, v[70:71], off
	v_or_b32_e32 v70, 0x87, v144
	v_ashrrev_i32_e32 v71, 31, v70
	v_lshlrev_b64 v[70:71], 6, v[70:71]
	v_ashrrev_i32_e32 v68, 3, v68
	v_lshl_add_u64 v[70:71], v[136:137], 0, v[70:71]
	v_ashrrev_i32_e32 v69, 31, v68
	global_load_dword v73, v[70:71], off
	v_lshlrev_b64 v[70:71], 14, v[68:69]
	s_waitcnt vmcnt(7)
	s_nop 1
	v_mov_b32_dpp v68, v76 quad_perm:[1,0,3,2] row_mask:0xf bank_mask:0xf
	s_waitcnt vmcnt(6)
	s_nop 1
	v_mov_b32_dpp v69, v77 quad_perm:[1,0,3,2] row_mask:0xf bank_mask:0xf
	s_waitcnt lgkmcnt(0)
	v_pk_add_f32 v[68:69], v[76:77], v[68:69]
	s_nop 1
	v_mov_b32_dpp v76, v68 quad_perm:[2,3,0,1] row_mask:0xf bank_mask:0xf
	v_mov_b32_dpp v77, v69 quad_perm:[2,3,0,1] row_mask:0xf bank_mask:0xf
	s_waitcnt lgkmcnt(0)
	v_pk_add_f32 v[68:69], v[68:69], v[76:77]
	s_nop 1
	v_mov_b32_dpp v76, v68 row_half_mirror row_mask:0xf bank_mask:0xf
	v_mov_b32_dpp v77, v69 row_half_mirror row_mask:0xf bank_mask:0xf
	s_waitcnt lgkmcnt(0)
	v_pk_add_f32 v[68:69], v[68:69], v[76:77]
	s_nop 1
	v_mov_b32_dpp v76, v68 row_mirror row_mask:0xf bank_mask:0xf
	v_mov_b32_dpp v77, v69 row_mirror row_mask:0xf bank_mask:0xf
	s_waitcnt lgkmcnt(0)
	v_pk_add_f32 v[68:69], v[68:69], v[76:77]
	s_nop 0
	v_pk_fma_f32 v[68:69], v[68:69], s[34:35], v[142:143] op_sel_hi:[1,0,0]
	s_nop 0
	v_mul_f32_e32 v76, 0x4b800000, v68
	v_cmp_gt_f32_e64 s[2:3], s25, v68
	v_cmp_gt_f32_e32 vcc, s25, v69
	s_nop 0
	v_cndmask_b32_e64 v68, v68, v76, s[2:3]
	v_mul_f32_e32 v76, 0x4b800000, v69
	v_cndmask_b32_e32 v69, v69, v76, vcc
	v_rsq_f32_e32 v68, v68
	v_rsq_f32_e32 v69, v69
	s_nop 0
	v_pk_mul_f32 v[76:77], v[68:69], s[26:27] op_sel_hi:[1,0]
	s_nop 0
	v_cndmask_b32_e32 v69, v69, v77, vcc
	v_cndmask_b32_e64 v68, v68, v76, s[2:3]
	s_waitcnt vmcnt(5)
	s_nop 1
	v_mov_b32_dpp v76, v80 quad_perm:[1,0,3,2] row_mask:0xf bank_mask:0xf
	s_waitcnt vmcnt(4)
	s_nop 1
	v_mov_b32_dpp v77, v81 quad_perm:[1,0,3,2] row_mask:0xf bank_mask:0xf
	v_pk_mul_f32 v[62:63], v[62:63], v[68:69]
	v_pk_mul_f32 v[54:55], v[54:55], v[68:69]
	v_cvt_pk_bf16_f32 v62, v62, v63
	v_pk_mul_f32 v[46:47], v[46:47], v[68:69]
	s_waitcnt lgkmcnt(0)
	v_pk_add_f32 v[76:77], v[80:81], v[76:77]
	s_nop 1
	v_mov_b32_dpp v80, v76 quad_perm:[2,3,0,1] row_mask:0xf bank_mask:0xf
	v_mov_b32_dpp v81, v77 quad_perm:[2,3,0,1] row_mask:0xf bank_mask:0xf
	v_pk_mul_f32 v[38:39], v[38:39], v[68:69]
	v_pk_mul_f32 v[30:31], v[30:31], v[68:69]
	v_pk_mul_f32 v[22:23], v[22:23], v[68:69]
	v_pk_mul_f32 v[14:15], v[14:15], v[68:69]
	s_waitcnt lgkmcnt(0)
	v_pk_add_f32 v[76:77], v[76:77], v[80:81]
	s_nop 1
	v_mov_b32_dpp v80, v76 row_half_mirror row_mask:0xf bank_mask:0xf
	v_mov_b32_dpp v81, v77 row_half_mirror row_mask:0xf bank_mask:0xf
	v_pk_mul_f32 v[6:7], v[6:7], v[68:69]
	v_cvt_pk_bf16_f32 v54, v54, v55
	v_cvt_pk_bf16_f32 v46, v46, v47
	v_cvt_pk_bf16_f32 v38, v38, v39
	s_waitcnt lgkmcnt(0)
	v_pk_add_f32 v[76:77], v[76:77], v[80:81]
	s_nop 1
	v_mov_b32_dpp v80, v76 row_mirror row_mask:0xf bank_mask:0xf
	v_mov_b32_dpp v81, v77 row_mirror row_mask:0xf bank_mask:0xf
	v_cvt_pk_bf16_f32 v30, v30, v31
	v_cvt_pk_bf16_f32 v22, v22, v23
	v_cvt_pk_bf16_f32 v14, v14, v15
	v_cvt_pk_bf16_f32 v6, v6, v7
	s_waitcnt lgkmcnt(0)
; DI unsigned pk2(float lo, float hi) { return pg8::cvt_pk_bf16(lo, hi); }
;     DI void operator()(const f32x4 (&acc)[2][2][4][2], const pg8::Unit& u, int wr, int wc, int fr, int fq) const {
;     ...
;         for (int bj = 0; bj < 2; ++bj) {
;             float rs[8];
; #pragma unroll
;             for (int j = 0; j < 8; ++j) {
;                 float s = ssq[(size_t)(tok0 + bj * 128 + j) * 16 + fr];
;                 s += __shfl_xor(s, 1); s += __shfl_xor(s, 2); s += __shfl_xor(s, 4); s += __shfl_xor(s, 8);
;                 rs[j] = rsqrtf(s * (1.0f / DM) + EPS);
;             }
; #pragma unroll
;             for (int ai = 0; ai < 2; ++ai)
; #pragma unroll
;                 for (int m = 0; m < 4; ++m) {
;                     const f32x4 a = acc[ai][bj][m][0], b = acc[ai][bj][m][1];
;                     u32x4 w; w.x = pk2(a[0] * rs[0], a[1] * rs[1]); w.y = pk2(a[2] * rs[2], a[3] * rs[3]); w.z = pk2(b[0] * rs[4], b[1] * rs[5]); w.w = pk2(b[2] * rs[6], b[3] * rs[7]);
;                     *(u32x4*)(VT + ((size_t)((tok0 + bj * 128) >> 3) * 1024 + (row0 + ai * 128 + m * 16)) * 8) = w;
;                 }
;         }
	v_pk_add_f32 v[76:77], v[76:77], v[80:81]
	s_nop 0
	v_pk_fma_f32 v[76:77], v[76:77], s[34:35], v[142:143] op_sel_hi:[1,0,0]
	s_nop 0
	v_mul_f32_e32 v63, 0x4b800000, v76
	v_cmp_gt_f32_e64 s[2:3], s25, v76
	v_cmp_gt_f32_e32 vcc, s25, v77
	s_nop 0
	v_cndmask_b32_e64 v63, v76, v63, s[2:3]
	v_rsq_f32_e32 v76, v63
	v_mul_f32_e32 v63, 0x4b800000, v77
	v_cndmask_b32_e32 v63, v77, v63, vcc
	v_rsq_f32_e32 v77, v63
	s_nop 0
	v_pk_mul_f32 v[80:81], v[76:77], s[26:27] op_sel_hi:[1,0]
	s_nop 0
	v_cndmask_b32_e32 v77, v77, v81, vcc
	v_cndmask_b32_e64 v76, v76, v80, s[2:3]
	v_pk_mul_f32 v[64:65], v[64:65], v[76:77]
	v_pk_mul_f32 v[56:57], v[56:57], v[76:77]
	v_cvt_pk_bf16_f32 v63, v64, v65
	s_waitcnt vmcnt(3)
	s_nop 1
	v_mov_b32_dpp v64, v78 quad_perm:[1,0,3,2] row_mask:0xf bank_mask:0xf
	s_waitcnt vmcnt(2)
	s_nop 1
	v_mov_b32_dpp v65, v79 quad_perm:[1,0,3,2] row_mask:0xf bank_mask:0xf
	v_pk_mul_f32 v[48:49], v[48:49], v[76:77]
	v_pk_mul_f32 v[40:41], v[40:41], v[76:77]
	v_pk_mul_f32 v[32:33], v[32:33], v[76:77]
	v_pk_mul_f32 v[24:25], v[24:25], v[76:77]
	s_waitcnt lgkmcnt(0)
	v_pk_add_f32 v[64:65], v[78:79], v[64:65]
	s_nop 1
	v_mov_b32_dpp v78, v64 quad_perm:[2,3,0,1] row_mask:0xf bank_mask:0xf
	v_mov_b32_dpp v79, v65 quad_perm:[2,3,0,1] row_mask:0xf bank_mask:0xf
	v_pk_mul_f32 v[16:17], v[16:17], v[76:77]
	v_pk_mul_f32 v[8:9], v[8:9], v[76:77]
	v_cvt_pk_bf16_f32 v55, v56, v57
	v_cvt_pk_bf16_f32 v47, v48, v49
	s_waitcnt lgkmcnt(0)
	v_pk_add_f32 v[64:65], v[64:65], v[78:79]
	s_nop 1
	v_mov_b32_dpp v78, v64 row_half_mirror row_mask:0xf bank_mask:0xf
	v_mov_b32_dpp v79, v65 row_half_mirror row_mask:0xf bank_mask:0xf
	v_cvt_pk_bf16_f32 v39, v40, v41
	v_cvt_pk_bf16_f32 v31, v32, v33
	v_cvt_pk_bf16_f32 v23, v24, v25
	v_cvt_pk_bf16_f32 v15, v16, v17
	s_waitcnt lgkmcnt(0)
	v_pk_add_f32 v[64:65], v[64:65], v[78:79]
	s_nop 1
	v_mov_b32_dpp v78, v64 row_mirror row_mask:0xf bank_mask:0xf
	v_mov_b32_dpp v79, v65 row_mirror row_mask:0xf bank_mask:0xf
	v_cvt_pk_bf16_f32 v7, v8, v9
	s_waitcnt lgkmcnt(0)
	v_pk_add_f32 v[64:65], v[64:65], v[78:79]
	s_nop 0
	v_pk_fma_f32 v[64:65], v[64:65], s[34:35], v[142:143] op_sel_hi:[1,0,0]
	s_nop 0
	v_mul_f32_e32 v78, 0x4b800000, v64
	v_cmp_gt_f32_e64 s[2:3], s25, v64
	v_cmp_gt_f32_e32 vcc, s25, v65
	s_nop 0
	v_cndmask_b32_e64 v64, v64, v78, s[2:3]
	v_mul_f32_e32 v78, 0x4b800000, v65
	v_cndmask_b32_e32 v65, v65, v78, vcc
	v_rsq_f32_e32 v64, v64
	v_rsq_f32_e32 v65, v65
	s_nop 0
	v_pk_mul_f32 v[78:79], v[64:65], s[26:27] op_sel_hi:[1,0]
	s_nop 0
	v_cndmask_b32_e32 v79, v65, v79, vcc
	v_cndmask_b32_e64 v78, v64, v78, s[2:3]
	v_pk_mul_f32 v[58:59], v[58:59], v[78:79]
	v_pk_mul_f32 v[50:51], v[50:51], v[78:79]
	v_cvt_pk_bf16_f32 v64, v58, v59
	s_waitcnt vmcnt(1)
	s_nop 1
	v_mov_b32_dpp v58, v72 quad_perm:[1,0,3,2] row_mask:0xf bank_mask:0xf
	s_waitcnt vmcnt(0)
	s_nop 1
	v_mov_b32_dpp v59, v73 quad_perm:[1,0,3,2] row_mask:0xf bank_mask:0xf
	v_pk_mul_f32 v[42:43], v[42:43], v[78:79]
	v_pk_mul_f32 v[34:35], v[34:35], v[78:79]
	v_pk_mul_f32 v[26:27], v[26:27], v[78:79]
	v_pk_mul_f32 v[18:19], v[18:19], v[78:79]
	s_waitcnt lgkmcnt(0)
	v_pk_add_f32 v[58:59], v[72:73], v[58:59]
	s_nop 1
	v_mov_b32_dpp v72, v58 quad_perm:[2,3,0,1] row_mask:0xf bank_mask:0xf
	v_mov_b32_dpp v73, v59 quad_perm:[2,3,0,1] row_mask:0xf bank_mask:0xf
	v_pk_mul_f32 v[10:11], v[10:11], v[78:79]
	v_pk_mul_f32 v[2:3], v[2:3], v[78:79]
	v_cvt_pk_bf16_f32 v56, v50, v51
	v_cvt_pk_bf16_f32 v48, v42, v43
	s_waitcnt lgkmcnt(0)
	v_pk_add_f32 v[58:59], v[58:59], v[72:73]
	s_nop 1
	v_mov_b32_dpp v72, v58 row_half_mirror row_mask:0xf bank_mask:0xf
	v_mov_b32_dpp v73, v59 row_half_mirror row_mask:0xf bank_mask:0xf
	v_cvt_pk_bf16_f32 v40, v34, v35
	v_cvt_pk_bf16_f32 v32, v26, v27
	v_cvt_pk_bf16_f32 v24, v18, v19
	v_cvt_pk_bf16_f32 v16, v10, v11
	s_waitcnt lgkmcnt(0)
	v_pk_add_f32 v[58:59], v[58:59], v[72:73]
	s_nop 1
	v_mov_b32_dpp v72, v58 row_mirror row_mask:0xf bank_mask:0xf
	v_mov_b32_dpp v73, v59 row_mirror row_mask:0xf bank_mask:0xf
	v_cvt_pk_bf16_f32 v8, v2, v3
	s_waitcnt lgkmcnt(0)
	v_pk_add_f32 v[58:59], v[58:59], v[72:73]
	s_nop 0
	v_pk_fma_f32 v[58:59], v[58:59], s[34:35], v[142:143] op_sel_hi:[1,0,0]
	s_nop 0
	v_mul_f32_e32 v65, 0x4b800000, v58
	v_cmp_gt_f32_e64 s[2:3], s25, v58
	v_cmp_gt_f32_e32 vcc, s25, v59
	s_nop 0
	v_cndmask_b32_e64 v58, v58, v65, s[2:3]
	v_mul_f32_e32 v65, 0x4b800000, v59
	v_cndmask_b32_e32 v59, v59, v65, vcc
	v_rsq_f32_e32 v58, v58
	v_rsq_f32_e32 v59, v59
	s_nop 0
	v_pk_mul_f32 v[72:73], v[58:59], s[26:27] op_sel_hi:[1,0]
	s_nop 0
	v_cndmask_b32_e32 v59, v59, v73, vcc
	v_cndmask_b32_e64 v58, v58, v72, s[2:3]
	v_pk_mul_f32 v[60:61], v[60:61], v[58:59]
	v_pk_mul_f32 v[50:51], v[52:53], v[58:59]
	v_cvt_pk_bf16_f32 v65, v60, v61
	v_lshl_add_u64 v[60:61], s[12:13], 0, v[70:71]
	v_pk_mul_f32 v[42:43], v[44:45], v[58:59]
	v_pk_mul_f32 v[34:35], v[36:37], v[58:59]
	v_pk_mul_f32 v[26:27], v[28:29], v[58:59]
	v_pk_mul_f32 v[18:19], v[20:21], v[58:59]
	v_pk_mul_f32 v[10:11], v[12:13], v[58:59]
	v_pk_mul_f32 v[2:3], v[4:5], v[58:59]
	v_lshl_add_u64 v[70:71], v[60:61], 0, v[122:123]
	v_cvt_pk_bf16_f32 v57, v50, v51
	v_lshl_add_u64 v[50:51], v[60:61], 0, v[114:115]
	v_cvt_pk_bf16_f32 v49, v42, v43
	v_lshl_add_u64 v[42:43], v[60:61], 0, v[106:107]
	v_cvt_pk_bf16_f32 v41, v34, v35
	v_lshl_add_u64 v[34:35], v[60:61], 0, v[98:99]
	v_cvt_pk_bf16_f32 v33, v26, v27
	v_lshl_add_u64 v[26:27], v[60:61], 0, v[90:91]
	v_cvt_pk_bf16_f32 v25, v18, v19
	v_lshl_add_u64 v[18:19], v[60:61], 0, v[82:83]
	v_cvt_pk_bf16_f32 v17, v10, v11
	v_lshl_add_u64 v[10:11], v[60:61], 0, v[74:75]
	v_cvt_pk_bf16_f32 v9, v2, v3
	v_lshl_add_u64 v[2:3], v[60:61], 0, v[66:67]
	s_mov_b64 s[2:3], -1
	s_andn2_b64 vcc, exec, s[42:43]
	global_store_dwordx4 v[70:71], v[62:65], off
	global_store_dwordx4 v[50:51], v[54:57], off
	global_store_dwordx4 v[42:43], v[46:49], off
	global_store_dwordx4 v[34:35], v[38:41], off
	global_store_dwordx4 v[26:27], v[30:33], off
	global_store_dwordx4 v[18:19], v[22:25], off
	global_store_dwordx4 v[10:11], v[14:17], off
	global_store_dwordx4 v[2:3], v[6:9], off
	s_cbranch_vccnz .LBB0_424
	s_andn2_b64 vcc, exec, s[38:39]
	s_cbranch_vccnz .LBB0_423
	s_barrier
	s_branch .LBB0_423
